# O3 L3: swapped MFMA operand roles + B-tile row permutation so epilogue lanes own 4 consecutive cols; residual load/f32 store fully coalesced, no transpose
# speedup vs baseline: 1.0190x; 1.0067x over previous
; #define PG8_STAGE(bufoff, gbase, voff) do { _Pragma("unroll") for (int _i = 0; _i < 2; ++_i) \
;         __builtin_amdgcn_global_load_lds((const unsigned*)((const char*)(gbase) + (voff)[_i]), (LAS unsigned*)(lds + (bufoff) + ldsw + _i * 8192), 16, 0, 0); } while (0)
; #define PG8_WAIT_V(n) asm volatile("s_waitcnt vmcnt(" #n ")" ::: "memory")
; #define PG8_BAR __builtin_amdgcn_s_barrier()
; template <class Epi, class Sched>
; __device__ __forceinline__ void gemm_phase(LAS unsigned char* lds, const int K, const int lda, const int ldb, const Sched& S, const Epi& E) {
;     ...
;     const int wid = __builtin_amdgcn_readfirstlane(tid >> 6), lane = tid & 63, wr = wid >> 2, wc = wid & 3, fr = lane & 15, fq = lane >> 4;
;     const int nt = K / BK;
;     unsigned voffA[2], voffB[2];
; #pragma unroll
;     for (int i = 0; i < 2; ++i) { int R, C; stage_rc(tid * 16 + i * 8192, R, C); const int Rb = (R & ~31) + perm32(R & 31);
;         voffA[i] = (unsigned)(R * lda + C) * 2u; voffB[i] = (unsigned)(Rb * ldb + C) * 2u; }
;     const size_t kstep = (size_t)(BK * 2);
;     const size_t hA = (size_t)HALF * lda * 2, hB = (size_t)HALF * ldb * 2;
;     const unsigned ldsw = (unsigned)wid * 1024u;
;     const int aoff = lds_byte(wr * 64 + fr, fq * 8), boff = lds_byte(wc * 32 + fr, fq * 8);
;     ...
;     Unit cur, nxt; int ui = 0;
;     if (!S.next(0, cur)) return;
;     f32x4 acc[2][2][4][2];
; #pragma unroll
;     for (int a = 0; a < 2; ++a)
; #pragma unroll
;         for (int b = 0; b < 2; ++b)
; #pragma unroll
;             for (int m = 0; m < 4; ++m)
; #pragma unroll
;                 for (int n = 0; n < 2; ++n) acc[a][b][m][n] = (f32x4){0.f, 0.f, 0.f, 0.f};
;     bf16x8 At[4][2], B0[2][2], B1[2][2];
;     const char* cA = S.aptr(cur); const char* cB = S.bptr(cur);
;     PG8_STAGE(PG8_SB(0, 0), cB, voffB); PG8_STAGE(PG8_SB(0, 1), cB + hB, voffB); PG8_STAGE(PG8_SA(0, 0), cA, voffA); PG8_STAGE(PG8_SA(0, 1), cA + hA, voffA);
;     if (wr == 1) PG8_BAR;
;     PG8_WAIT_V(2); PG8_BAR;
;     PG8_STAGE(PG8_SB(1, 0), cB + kstep, voffB); PG8_STAGE(PG8_SA(1, 0), cA + kstep, voffA); PG8_STAGE(PG8_SB(1, 1), cB + hB + kstep, voffB);
;     PG8_WAIT_V(6); PG8_BAR;
.LBB0_1613:
	v_ashrrev_i32_e32 v1, 31, v254
	v_lshrrev_b32_e32 v1, 26, v1
	v_add_u32_e32 v1, v254, v1
	v_ashrrev_i32_e32 v8, 6, v1
	v_bfe_i32 v1, v254, 27, 1
	v_lshlrev_b32_e32 v0, 4, v254
	v_lshrrev_b32_e32 v1, 22, v1
	v_add_u32_e32 v1, v0, v1
	v_and_b32_e32 v1, 0xfffffc00, v1
	v_sub_u32_e32 v1, v0, v1
	v_lshrrev_b32_e32 v2, 4, v1
	v_bitop3_b32 v1, v2, v1, 32 bitop3:0x6c
	v_ashrrev_i32_e32 v3, 31, v1
	v_lshrrev_b32_e32 v3, 26, v3
	v_add_u32_e32 v3, v1, v3
	v_lshlrev_b32_e32 v2, 3, v8
	v_ashrrev_i32_e32 v9, 6, v3
	v_and_b32_e32 v3, 0xc0, v3
	v_and_b32_e32 v2, -16, v2
	v_sub_u32_e32 v1, v1, v3
	v_mov_b32_e32 v3, 1
	v_add_u32_e32 v2, v9, v2
	v_ashrrev_i16_sdwa v1, v3, sext(v1) dst_sel:DWORD dst_unused:UNUSED_PAD src0_sel:DWORD src1_sel:BYTE_0
	v_lshlrev_b32_e32 v4, 5, v8
	v_bfe_i32 v10, v1, 0, 16
	v_lshlrev_b32_e32 v1, 1, v2
	v_lshrrev_b32_e32 v5, 2, v2
	v_and_b32_e32 v6, 3, v9
	s_mov_b32 s5, 0xfffe0
	v_and_b32_e32 v4, 32, v4
	v_and_b32_e32 v1, 24, v1
	v_and_b32_e32 v5, 4, v5
	v_and_or_b32 v6, v2, s5, v6
	v_or3_b32 v1, v6, v5, v1
	v_add_lshl_u32 v4, v4, v10, 1
	v_add_u32_e32 v0, 0x2000, v0
	v_and_b32_e32 v248, 63, v254
	v_lshrrev_b32_e32 v249, 5, v248
	v_lshlrev_b32_e32 v249, 1, v249
	v_xor_b32_e32 v248, v248, v249
	v_lshrrev_b32_e32 v249, 2, v248
	v_and_b32_e32 v248, 3, v248
	v_lshrrev_b32_e32 v250, 6, v254
	v_lshrrev_b32_e32 v251, 1, v250
	v_and_b32_e32 v250, 1, v250
	v_lshl_add_u32 v249, v249, 2, v251
	v_lshlrev_b32_e32 v249, 12, v249
	v_lshl_add_u32 v249, v250, 6, v249
	v_lshl_add_u32 v166, v248, 4, v249
	v_add_u32_e32 v252, 0x40000, v166
	v_ashrrev_i32_e32 v1, 31, v0
	v_lshrrev_b32_e32 v1, 22, v1
	v_add_u32_e32 v1, v0, v1
	v_ashrrev_i32_e32 v11, 10, v1
	v_mul_i32_i24_e32 v1, 0x400, v11
	v_sub_u32_e32 v0, v0, v1
	v_lshrrev_b32_e32 v1, 4, v0
	v_bitop3_b32 v0, v1, v0, 32 bitop3:0x6c
	v_lshl_add_u32 v164, v2, 12, v4
	v_ashrrev_i32_e32 v2, 31, v0
	v_lshrrev_b32_e32 v2, 26, v2
	v_add_u32_e32 v2, v0, v2
	v_lshlrev_b32_e32 v1, 3, v11
	v_ashrrev_i32_e32 v12, 6, v2
	v_and_b32_e32 v2, 0xc0, v2
	v_and_b32_e32 v1, -16, v1
	v_sub_u32_e32 v0, v0, v2
	v_add_u32_e32 v1, v12, v1
	v_ashrrev_i16_sdwa v0, v3, sext(v0) dst_sel:DWORD dst_unused:UNUSED_PAD src0_sel:DWORD src1_sel:BYTE_0
	v_and_b32_e32 v3, 3, v12
	s_add_i32 s4, s6, s4
	v_and_or_b32 v3, v1, s5, v3
	s_ashr_i32 s5, s4, 31
	s_lshr_b32 s5, s5, 26
	s_add_i32 s5, s4, s5
	s_ashr_i32 s6, s5, 6
	s_and_b32 s5, s5, 0xffc0
	s_sub_i32 s4, s4, s5
	s_bfe_i32 s5, s4, 0x80000
	s_bfe_u32 s5, s5, 0x3000c
	s_add_i32 s5, s4, s5
	s_bfe_i32 s7, s5, 0x80000
	s_and_b32 s5, s5, 0xf8
	s_sub_i32 s4, s4, s5
	s_lshl_b32 s6, s6, 3
	s_sext_i32_i16 s7, s7
	s_sext_i32_i8 s4, s4
	s_lshr_b32 s14, s7, 3
	s_add_i32 s26, s6, s4
	s_ashr_i32 s10, s0, 6
	s_ashr_i32 s27, s26, 31
	s_bfe_i64 s[6:7], s[14:15], 0x100000
	s_ashr_i32 s1, s0, 8
	s_lshl_b32 s36, s10, 10
	s_lshl_b64 s[4:5], s[26:27], 20
	s_lshl_b64 s[6:7], s[6:7], 20
	s_add_u32 s28, s12, s6
	v_lshlrev_b32_e32 v4, 5, v11
	v_bfe_i32 v13, v0, 0, 16
	v_lshlrev_b32_e32 v0, 1, v1
	v_lshrrev_b32_e32 v2, 2, v1
	s_addc_u32 s29, s13, s7
	s_add_i32 s27, s36, 0
	v_and_b32_e32 v4, 32, v4
	v_and_b32_e32 v0, 24, v0
	v_and_b32_e32 v2, 4, v2
	s_add_i32 m0, s27, 0x10000
	v_or3_b32 v0, v3, v2, v0
	v_add_lshl_u32 v2, v4, v13, 1
	global_load_lds_dwordx4 v166, s[28:29]
	s_add_i32 m0, s27, 0x12000
	v_mov_b32_e32 v170, v252
	s_add_u32 s6, s28, 0x80000
	global_load_lds_dwordx4 v170, s[28:29]
	s_addc_u32 s7, s29, 0
	s_add_i32 m0, s27, 0x14000
	v_lshl_add_u32 v168, v1, 12, v2
	global_load_lds_dwordx4 v166, s[6:7]
	s_add_i32 m0, s27, 0x16000
	s_add_u32 s30, s8, s4
	s_addc_u32 s31, s9, s5
	s_add_i32 s37, s27, 0x2000
	global_load_lds_dwordx4 v170, s[6:7]
	s_mov_b32 m0, s27
	s_add_u32 s4, s30, 0x80000
	global_load_lds_dwordx4 v164, s[30:31]
	s_mov_b32 m0, s37
	s_addc_u32 s5, s31, 0
	s_add_i32 s38, s27, 0x4000
	global_load_lds_dwordx4 v168, s[30:31]
	s_mov_b32 m0, s38
	s_add_i32 s39, s27, 0x6000
	global_load_lds_dwordx4 v164, s[4:5]
	s_mov_b32 m0, s39
	v_mov_b32_e32 v167, 0
	global_load_lds_dwordx4 v168, s[4:5]
	s_load_dwordx2 s[4:5], s[82:83], 0x88
	v_mov_b32_e32 v171, v167
	v_mov_b32_e32 v165, v167
	v_mov_b32_e32 v169, v167
	s_cmp_eq_u32 s1, 1
	s_mov_b32 s40, 0
	v_lshl_add_u64 v[6:7], s[28:29], 0, v[166:167]
	v_lshl_add_u64 v[4:5], s[28:29], 0, v[170:171]
	v_lshl_add_u64 v[0:1], s[30:31], 0, v[164:165]
	s_cselect_b64 s[6:7], -1, 0
	s_cmp_lg_u32 s1, 1
	v_lshl_add_u64 v[2:3], s[30:31], 0, v[168:169]
	s_cbranch_scc1 .LBB0_1615
	s_barrier
.LBB0_1615:
	s_lshl_b32 s10, s10, 5
	s_and_b32 s20, s10, 0x60
	s_mov_b64 s[10:11], 0x80
	s_add_i32 m0, s27, 0x18000
	v_lshl_add_u64 v[6:7], v[6:7], 0, s[10:11]
	s_lshl_b32 s15, s1, 13
	s_lshl_b32 s21, s20, 8
	s_waitcnt vmcnt(2)
	s_barrier
	global_load_lds_dwordx4 v[6:7], off
	v_lshl_add_u64 v[4:5], v[4:5], 0, s[10:11]
	s_add_i32 m0, s27, 0x1a000
	s_add_i32 s41, s27, 0x8000
	s_add_i32 s42, s27, 0xa000
	global_load_lds_dwordx4 v[4:5], off
	v_lshl_add_u64 v[0:1], v[0:1], 0, s[10:11]
	s_mov_b32 m0, s41
	s_add_u32 s18, s28, 0x80080
	global_load_lds_dwordx4 v[0:1], off
	v_lshl_add_u64 v[0:1], v[2:3], 0, s[10:11]
	s_mov_b32 m0, s42
	s_addc_u32 s19, s29, 0
	global_load_lds_dwordx4 v[0:1], off
	s_add_i32 m0, s27, 0x1c000
	v_lshl_add_u64 v[0:1], s[18:19], 0, v[166:167]
	global_load_lds_dwordx4 v[0:1], off
	v_lshl_add_u64 v[0:1], s[18:19], 0, v[170:171]
	s_add_i32 m0, s27, 0x1e000
	s_cmpk_lt_u32 s0, 0x100
	global_load_lds_dwordx4 v[0:1], off
	v_lshrrev_b32_e32 v1, 1, v254
	v_and_b32_e32 v1, 24, v1
	v_and_b32_e32 v0, 15, v254
	v_lshlrev_b32_e32 v2, 1, v1
	v_lshl_or_b32 v194, s1, 6, v0
	v_lshl_or_b32 v0, v0, 6, v2
	v_lshlrev_b32_e32 v2, 2, v254
	v_and_b32_e32 v2, 32, v2
	v_bitop3_b32 v3, v0, s15, v2 bitop3:0xde
	v_bitop3_b32 v195, v0, s21, v2 bitop3:0xde
	v_lshlrev_b32_e32 v0, 15, v11
	v_and_b32_e32 v0, 0xffff0000, v0
	v_or_b32_e32 v196, s20, v1
	v_lshl_add_u32 v0, v12, 12, v0
	v_and_b32_e32 v1, 1, v11
	v_lshl_or_b32 v0, v1, 6, v0
	v_lshl_add_u32 v172, v13, 1, v0
	v_lshlrev_b32_e32 v0, 15, v8
	v_and_b32_e32 v0, 0xffff0000, v0
	s_waitcnt vmcnt(6)
	v_lshl_add_u32 v0, v9, 12, v0
	v_and_b32_e32 v1, 1, v8
	s_sext_i32_i8 s46, s14
	s_cselect_b64 s[14:15], -1, 0
	v_lshl_or_b32 v0, v1, 6, v0
	s_add_i32 s44, 0, 0x10000
	s_add_i32 s45, 0, 0x14000
	s_ashr_i32 s43, s3, 31
	v_mov_b32_e32 v173, v167
	v_lshl_add_u32 v174, v10, 1, v0
	v_mov_b32_e32 v175, v167
	v_mov_b64_e32 v[176:177], 0x400
	v_mov_b64_e32 v[178:179], 0x3ff
	v_add_u32_e32 v197, s44, v195
	v_add_u32_e32 v198, 0x11000, v195
	v_add_u32_e32 v199, 0, v3
	s_barrier
	s_branch .LBB0_1618

; #define PG8_STAGE(bufoff, gbase, voff) do { _Pragma("unroll") for (int _i = 0; _i < 2; ++_i) \
;         __builtin_amdgcn_global_load_lds((const unsigned*)((const char*)(gbase) + (voff)[_i]), (LAS unsigned*)(lds + (bufoff) + ldsw + _i * 8192), 16, 0, 0); } while (0)
; #define PG8_LDA(dst, b, h) do { _Pragma("unroll") for (int m = 0; m < 4; ++m) _Pragma("unroll") for (int k = 0; k < 2; ++k) dst[m][k] = *(const LAS bf16x8*)(lds + PG8_SA(b, h) + aoff + m * 2048 + k * 1024); } while (0)
; #define PG8_LDB(dst, b, h) do { _Pragma("unroll") for (int n = 0; n < 2; ++n) _Pragma("unroll") for (int k = 0; k < 2; ++k) dst[n][k] = *(const LAS bf16x8*)(lds + PG8_SB(b, h) + boff + n * 2048 + k * 1024); } while (0)
; #define PG8_MMA(ai, bj, At, Bt) do { __builtin_amdgcn_s_setprio(1); _Pragma("unroll") for (int m = 0; m < 4; ++m) _Pragma("unroll") for (int n = 0; n < 2; ++n) _Pragma("unroll") for (int k = 0; k < 2; ++k) \
;         acc[ai][bj][m][n] = __builtin_amdgcn_mfma_f32_16x16x32_bf16(Bt[n][k], At[m][k], acc[ai][bj][m][n], 0, 0, 0); __builtin_amdgcn_s_setprio(0); } while (0)
; #define PG8_WAIT_V(n) asm volatile("s_waitcnt vmcnt(" #n ")" ::: "memory")
; #define PG8_WAIT_L(n) asm volatile("s_waitcnt lgkmcnt(" #n ")" ::: "memory")
; #define PG8_BAR __builtin_amdgcn_s_barrier()
; #define PG8_SCHED __builtin_amdgcn_sched_barrier(0)
; template <class Epi, class Sched>
; __device__ __forceinline__ void gemm_phase(LAS unsigned char* lds, const int K, const int lda, const int ldb, const Sched& S, const Epi& E) {
;     ...
;             PG8_LDB(B0, 0, 0); PG8_LDB(B1, 0, 1); PG8_SCHED; PG8_LDA(At, 0, 0); PG8_STAGE(PG8_SA(1, 1), a1 + hA, voffA);
;             PG8_WAIT_V(8); PG8_WAIT_L(0); PG8_BAR; PG8_MMA(0, 0, At, B0); PG8_MMA(0, 1, At, B1); PG8_BAR; PG8_SCHED;
;             PG8_LDA(At, 0, 1); PG8_STAGE(PG8_SB(0, 0), b2, voffB); PG8_STAGE(PG8_SB(0, 1), b2 + hB, voffB); PG8_STAGE(PG8_SA(0, 0), a2, voffA);
;             PG8_WAIT_V(8); PG8_WAIT_L(0); PG8_BAR; PG8_MMA(1, 0, At, B0); PG8_MMA(1, 1, At, B1); PG8_BAR; PG8_SCHED;
.LBB0_1625:
	ds_read_b128 v[128:131], v197
	ds_read_b128 v[132:135], v197 offset:1024
	ds_read_b128 v[136:139], v197 offset:2048
	ds_read_b128 v[140:143], v197 offset:3072
	ds_read_b128 v[144:147], v198
	ds_read_b128 v[148:151], v198 offset:1024
	ds_read_b128 v[152:155], v198 offset:2048
	ds_read_b128 v[156:159], v198 offset:3072
	s_add_u32 s30, s28, 0xfff80080
	s_addc_u32 s31, s29, -1
	s_cmp_eq_u32 s51, 28
	s_cselect_b32 s35, s21, s31
	s_cselect_b32 s34, s47, s30
	s_cselect_b32 s31, s19, s50
	s_cselect_b32 s30, s48, s49
	v_lshl_add_u64 v[192:193], s[28:29], 0, v[174:175]
	s_add_i32 m0, s27, 0xc000
	ds_read_b128 v[160:163], v199
	ds_read_b128 v[180:183], v199 offset:1024
	ds_read_b128 v[184:187], v199 offset:2048
	ds_read_b128 v[188:191], v199 offset:3072
	ds_read_b128 v[200:203], v199 offset:4096
	ds_read_b128 v[204:207], v199 offset:5120
	ds_read_b128 v[208:211], v199 offset:6144
	ds_read_b128 v[212:215], v199 offset:7168
	global_load_lds_dwordx4 v[192:193], off
	v_lshl_add_u64 v[192:193], s[28:29], 0, v[172:173]
	s_add_i32 m0, s27, 0xe000
	s_nop 0
	global_load_lds_dwordx4 v[192:193], off
	s_waitcnt vmcnt(8)
	s_waitcnt lgkmcnt(0)
	s_barrier
	s_setprio 1
	s_waitcnt lgkmcnt(0)
	v_mfma_f32_16x16x32_bf16 v[124:127], v[160:163], v[128:131], v[124:127]
	v_mfma_f32_16x16x32_bf16 v[120:123], v[160:163], v[136:139], v[120:123]
	v_mfma_f32_16x16x32_bf16 v[108:111], v[184:187], v[128:131], v[108:111]
	v_mfma_f32_16x16x32_bf16 v[104:107], v[184:187], v[136:139], v[104:107]
	v_mfma_f32_16x16x32_bf16 v[96:99], v[200:203], v[128:131], v[96:99]
	v_mfma_f32_16x16x32_bf16 v[88:91], v[200:203], v[136:139], v[88:91]
	v_mfma_f32_16x16x32_bf16 v[80:83], v[208:211], v[128:131], v[80:83]
	v_mfma_f32_16x16x32_bf16 v[72:75], v[208:211], v[136:139], v[72:75]
	v_mfma_f32_16x16x32_bf16 v[124:127], v[180:183], v[132:135], v[124:127]
	v_mfma_f32_16x16x32_bf16 v[120:123], v[180:183], v[140:143], v[120:123]
	v_mfma_f32_16x16x32_bf16 v[108:111], v[188:191], v[132:135], v[108:111]
	v_mfma_f32_16x16x32_bf16 v[104:107], v[188:191], v[140:143], v[104:107]
	v_mfma_f32_16x16x32_bf16 v[96:99], v[204:207], v[132:135], v[96:99]
	v_mfma_f32_16x16x32_bf16 v[88:91], v[204:207], v[140:143], v[88:91]
	v_mfma_f32_16x16x32_bf16 v[80:83], v[212:215], v[132:135], v[80:83]
	v_mfma_f32_16x16x32_bf16 v[72:75], v[212:215], v[140:143], v[72:75]
	s_setprio 0
	s_setprio 1
	v_mfma_f32_16x16x32_bf16 v[116:119], v[160:163], v[144:147], v[116:119]
	v_mfma_f32_16x16x32_bf16 v[112:115], v[160:163], v[152:155], v[112:115]
	v_mfma_f32_16x16x32_bf16 v[100:103], v[184:187], v[144:147], v[100:103]
	v_mfma_f32_16x16x32_bf16 v[92:95], v[184:187], v[152:155], v[92:95]
	v_mfma_f32_16x16x32_bf16 v[84:87], v[200:203], v[144:147], v[84:87]
	v_mfma_f32_16x16x32_bf16 v[76:79], v[200:203], v[152:155], v[76:79]
	v_mfma_f32_16x16x32_bf16 v[68:71], v[208:211], v[144:147], v[68:71]
	v_mfma_f32_16x16x32_bf16 v[64:67], v[208:211], v[152:155], v[64:67]
	v_mfma_f32_16x16x32_bf16 v[116:119], v[180:183], v[148:151], v[116:119]
	v_mfma_f32_16x16x32_bf16 v[112:115], v[180:183], v[156:159], v[112:115]
	v_mfma_f32_16x16x32_bf16 v[100:103], v[188:191], v[148:151], v[100:103]
	v_mfma_f32_16x16x32_bf16 v[92:95], v[188:191], v[156:159], v[92:95]
	v_mfma_f32_16x16x32_bf16 v[84:87], v[204:207], v[148:151], v[84:87]
	v_mfma_f32_16x16x32_bf16 v[76:79], v[204:207], v[156:159], v[76:79]
	v_mfma_f32_16x16x32_bf16 v[68:71], v[212:215], v[148:151], v[68:71]
	v_mfma_f32_16x16x32_bf16 v[64:67], v[212:215], v[156:159], v[64:67]
	s_setprio 0
	s_barrier
	s_add_i32 s52, s44, s36
	v_lshl_add_u64 v[192:193], s[30:31], 0, v[166:167]
	s_mov_b32 m0, s52
	ds_read_b128 v[160:163], v199 offset:16384
	ds_read_b128 v[180:183], v199 offset:17408
	ds_read_b128 v[184:187], v199 offset:18432
	ds_read_b128 v[188:191], v199 offset:19456
	ds_read_b128 v[200:203], v199 offset:20480
	ds_read_b128 v[204:207], v199 offset:21504
	ds_read_b128 v[208:211], v199 offset:22528
	ds_read_b128 v[212:215], v199 offset:23552
	global_load_lds_dwordx4 v[192:193], off
	s_add_i32 m0, s52, 0x2000
	s_add_u32 s52, s30, 0x80000
	v_lshl_add_u64 v[216:217], s[30:31], 0, v[170:171]
	s_addc_u32 s53, s31, 0
	s_add_i32 s54, s45, s36
	global_load_lds_dwordx4 v[216:217], off
	v_lshl_add_u64 v[218:219], s[52:53], 0, v[166:167]
	s_mov_b32 m0, s54
	v_lshl_add_u64 v[220:221], s[34:35], 0, v[168:169]
	global_load_lds_dwordx4 v[218:219], off
	v_lshl_add_u64 v[218:219], s[52:53], 0, v[170:171]
	s_add_i32 m0, s54, 0x2000
	s_nop 0
	global_load_lds_dwordx4 v[218:219], off
	v_lshl_add_u64 v[218:219], s[34:35], 0, v[164:165]
	s_mov_b32 m0, s27
	s_nop 0
	global_load_lds_dwordx4 v[218:219], off
	s_mov_b32 m0, s37
	s_nop 0
	global_load_lds_dwordx4 v[220:221], off
	s_waitcnt vmcnt(8)
	s_waitcnt lgkmcnt(0)
	s_barrier
; #define PG8_STAGE(bufoff, gbase, voff) do { _Pragma("unroll") for (int _i = 0; _i < 2; ++_i) \
;         __builtin_amdgcn_global_load_lds((const unsigned*)((const char*)(gbase) + (voff)[_i]), (LAS unsigned*)(lds + (bufoff) + ldsw + _i * 8192), 16, 0, 0); } while (0)
; #define PG8_LDA(dst, b, h) do { _Pragma("unroll") for (int m = 0; m < 4; ++m) _Pragma("unroll") for (int k = 0; k < 2; ++k) dst[m][k] = *(const LAS bf16x8*)(lds + PG8_SA(b, h) + aoff + m * 2048 + k * 1024); } while (0)
; #define PG8_LDB(dst, b, h) do { _Pragma("unroll") for (int n = 0; n < 2; ++n) _Pragma("unroll") for (int k = 0; k < 2; ++k) dst[n][k] = *(const LAS bf16x8*)(lds + PG8_SB(b, h) + boff + n * 2048 + k * 1024); } while (0)
; #define PG8_MMA(ai, bj, At, Bt) do { __builtin_amdgcn_s_setprio(1); _Pragma("unroll") for (int m = 0; m < 4; ++m) _Pragma("unroll") for (int n = 0; n < 2; ++n) _Pragma("unroll") for (int k = 0; k < 2; ++k) \
;         acc[ai][bj][m][n] = __builtin_amdgcn_mfma_f32_16x16x32_bf16(Bt[n][k], At[m][k], acc[ai][bj][m][n], 0, 0, 0); __builtin_amdgcn_s_setprio(0); } while (0)
; #define PG8_WAIT_V(n) asm volatile("s_waitcnt vmcnt(" #n ")" ::: "memory")
; #define PG8_WAIT_L(n) asm volatile("s_waitcnt lgkmcnt(" #n ")" ::: "memory")
; #define PG8_BAR __builtin_amdgcn_s_barrier()
; #define PG8_SCHED __builtin_amdgcn_sched_barrier(0)
; template <class Epi, class Sched>
; __device__ __forceinline__ void gemm_phase(LAS unsigned char* lds, const int K, const int lda, const int ldb, const Sched& S, const Epi& E) {
;     ...
;             PG8_WAIT_V(8); PG8_WAIT_L(0); PG8_BAR; PG8_MMA(1, 0, At, B0); PG8_MMA(1, 1, At, B1); PG8_BAR; PG8_SCHED;
;             PG8_LDB(B0, 1, 0); PG8_LDB(B1, 1, 1); PG8_SCHED; PG8_LDA(At, 1, 0); PG8_STAGE(PG8_SA(0, 1), a2 + hA, voffA);
;             PG8_WAIT_V(8); PG8_WAIT_L(0); PG8_BAR; PG8_MMA(0, 0, At, B0); PG8_MMA(0, 1, At, B1); PG8_BAR; PG8_SCHED;
;             PG8_LDA(At, 1, 1); PG8_STAGE(PG8_SB(1, 0), b3, voffB); PG8_STAGE(PG8_SB(1, 1), b3 + hB, voffB); PG8_STAGE(PG8_SA(1, 0), a3, voffA);
	s_setprio 1
	s_waitcnt lgkmcnt(0)
	v_mfma_f32_16x16x32_bf16 v[60:63], v[160:163], v[128:131], v[60:63]
	v_mfma_f32_16x16x32_bf16 v[56:59], v[160:163], v[136:139], v[56:59]
	v_mfma_f32_16x16x32_bf16 v[48:51], v[184:187], v[128:131], v[48:51]
	v_mfma_f32_16x16x32_bf16 v[40:43], v[184:187], v[136:139], v[40:43]
	v_mfma_f32_16x16x32_bf16 v[32:35], v[200:203], v[128:131], v[32:35]
	v_mfma_f32_16x16x32_bf16 v[24:27], v[200:203], v[136:139], v[24:27]
	v_mfma_f32_16x16x32_bf16 v[16:19], v[208:211], v[128:131], v[16:19]
	v_mfma_f32_16x16x32_bf16 v[8:11], v[208:211], v[136:139], v[8:11]
	v_mfma_f32_16x16x32_bf16 v[60:63], v[180:183], v[132:135], v[60:63]
	v_mfma_f32_16x16x32_bf16 v[56:59], v[180:183], v[140:143], v[56:59]
	v_mfma_f32_16x16x32_bf16 v[48:51], v[188:191], v[132:135], v[48:51]
	v_mfma_f32_16x16x32_bf16 v[40:43], v[188:191], v[140:143], v[40:43]
	v_mfma_f32_16x16x32_bf16 v[32:35], v[204:207], v[132:135], v[32:35]
	v_mfma_f32_16x16x32_bf16 v[24:27], v[204:207], v[140:143], v[24:27]
	v_mfma_f32_16x16x32_bf16 v[16:19], v[212:215], v[132:135], v[16:19]
	v_mfma_f32_16x16x32_bf16 v[8:11], v[212:215], v[140:143], v[8:11]
	s_setprio 0
	s_setprio 1
	v_mfma_f32_16x16x32_bf16 v[52:55], v[160:163], v[144:147], v[52:55]
	v_mfma_f32_16x16x32_bf16 v[44:47], v[160:163], v[152:155], v[44:47]
	v_mfma_f32_16x16x32_bf16 v[36:39], v[184:187], v[144:147], v[36:39]
	v_mfma_f32_16x16x32_bf16 v[28:31], v[184:187], v[152:155], v[28:31]
	v_mfma_f32_16x16x32_bf16 v[20:23], v[200:203], v[144:147], v[20:23]
	v_mfma_f32_16x16x32_bf16 v[12:15], v[200:203], v[152:155], v[12:15]
	v_mfma_f32_16x16x32_bf16 v[4:7], v[208:211], v[144:147], v[4:7]
	v_mfma_f32_16x16x32_bf16 v[0:3], v[208:211], v[152:155], v[0:3]
	v_mfma_f32_16x16x32_bf16 v[52:55], v[180:183], v[148:151], v[52:55]
	v_mfma_f32_16x16x32_bf16 v[44:47], v[180:183], v[156:159], v[44:47]
	v_mfma_f32_16x16x32_bf16 v[36:39], v[188:191], v[148:151], v[36:39]
	v_mfma_f32_16x16x32_bf16 v[28:31], v[188:191], v[156:159], v[28:31]
	v_mfma_f32_16x16x32_bf16 v[20:23], v[204:207], v[148:151], v[20:23]
	v_mfma_f32_16x16x32_bf16 v[12:15], v[204:207], v[156:159], v[12:15]
	v_mfma_f32_16x16x32_bf16 v[4:7], v[212:215], v[148:151], v[4:7]
	v_mfma_f32_16x16x32_bf16 v[0:3], v[212:215], v[156:159], v[0:3]
	s_setprio 0
	s_barrier
	s_add_i32 s52, 0, 0x18000
	s_add_i32 s53, 0, 0x1c000
	v_add_u32_e32 v140, s52, v195
	v_add_u32_e32 v156, 0x19000, v195
	ds_read_b128 v[128:131], v140
	ds_read_b128 v[132:135], v140 offset:1024
	ds_read_b128 v[136:139], v140 offset:2048
	ds_read_b128 v[140:143], v140 offset:3072
	ds_read_b128 v[144:147], v156
	ds_read_b128 v[148:151], v156 offset:1024
	ds_read_b128 v[152:155], v156 offset:2048
	ds_read_b128 v[156:159], v156 offset:3072
	s_add_u32 s34, s34, 0x80000
	s_addc_u32 s35, s35, 0
	s_mov_b32 m0, s38
	v_lshl_add_u64 v[222:223], s[34:35], 0, v[164:165]
	ds_read_b128 v[160:163], v199 offset:32768
	ds_read_b128 v[180:183], v199 offset:33792
	ds_read_b128 v[184:187], v199 offset:34816
	ds_read_b128 v[188:191], v199 offset:35840
	ds_read_b128 v[200:203], v199 offset:36864
	ds_read_b128 v[204:207], v199 offset:37888
	ds_read_b128 v[208:211], v199 offset:38912
	ds_read_b128 v[212:215], v199 offset:39936
	global_load_lds_dwordx4 v[222:223], off
	v_lshl_add_u64 v[222:223], s[34:35], 0, v[168:169]
	s_mov_b32 m0, s39
	s_nop 0
	global_load_lds_dwordx4 v[222:223], off
	s_waitcnt vmcnt(8)
	s_waitcnt lgkmcnt(0)
	s_barrier
	s_setprio 1
	s_waitcnt lgkmcnt(0)
	v_mfma_f32_16x16x32_bf16 v[124:127], v[160:163], v[128:131], v[124:127]
	v_mfma_f32_16x16x32_bf16 v[120:123], v[160:163], v[136:139], v[120:123]
	v_mfma_f32_16x16x32_bf16 v[108:111], v[184:187], v[128:131], v[108:111]
	v_mfma_f32_16x16x32_bf16 v[104:107], v[184:187], v[136:139], v[104:107]
	v_mfma_f32_16x16x32_bf16 v[96:99], v[200:203], v[128:131], v[96:99]
	v_mfma_f32_16x16x32_bf16 v[88:91], v[200:203], v[136:139], v[88:91]
	v_mfma_f32_16x16x32_bf16 v[80:83], v[208:211], v[128:131], v[80:83]
	v_mfma_f32_16x16x32_bf16 v[72:75], v[208:211], v[136:139], v[72:75]
	v_mfma_f32_16x16x32_bf16 v[124:127], v[180:183], v[132:135], v[124:127]
	v_mfma_f32_16x16x32_bf16 v[120:123], v[180:183], v[140:143], v[120:123]
	v_mfma_f32_16x16x32_bf16 v[108:111], v[188:191], v[132:135], v[108:111]
	v_mfma_f32_16x16x32_bf16 v[104:107], v[188:191], v[140:143], v[104:107]
	v_mfma_f32_16x16x32_bf16 v[96:99], v[204:207], v[132:135], v[96:99]
	v_mfma_f32_16x16x32_bf16 v[88:91], v[204:207], v[140:143], v[88:91]
	v_mfma_f32_16x16x32_bf16 v[80:83], v[212:215], v[132:135], v[80:83]
	v_mfma_f32_16x16x32_bf16 v[72:75], v[212:215], v[140:143], v[72:75]
	s_setprio 0
	s_setprio 1
	v_mfma_f32_16x16x32_bf16 v[116:119], v[160:163], v[144:147], v[116:119]
	v_mfma_f32_16x16x32_bf16 v[112:115], v[160:163], v[152:155], v[112:115]
	v_mfma_f32_16x16x32_bf16 v[100:103], v[184:187], v[144:147], v[100:103]
	v_mfma_f32_16x16x32_bf16 v[92:95], v[184:187], v[152:155], v[92:95]
	v_mfma_f32_16x16x32_bf16 v[84:87], v[200:203], v[144:147], v[84:87]
	v_mfma_f32_16x16x32_bf16 v[76:79], v[200:203], v[152:155], v[76:79]
	v_mfma_f32_16x16x32_bf16 v[68:71], v[208:211], v[144:147], v[68:71]
	v_mfma_f32_16x16x32_bf16 v[64:67], v[208:211], v[152:155], v[64:67]
	v_mfma_f32_16x16x32_bf16 v[116:119], v[180:183], v[148:151], v[116:119]
	v_mfma_f32_16x16x32_bf16 v[112:115], v[180:183], v[156:159], v[112:115]
	v_mfma_f32_16x16x32_bf16 v[100:103], v[188:191], v[148:151], v[100:103]
	v_mfma_f32_16x16x32_bf16 v[92:95], v[188:191], v[156:159], v[92:95]
	v_mfma_f32_16x16x32_bf16 v[84:87], v[204:207], v[148:151], v[84:87]
	v_mfma_f32_16x16x32_bf16 v[76:79], v[204:207], v[156:159], v[76:79]
	v_mfma_f32_16x16x32_bf16 v[68:71], v[212:215], v[148:151], v[68:71]
	v_mfma_f32_16x16x32_bf16 v[64:67], v[212:215], v[156:159], v[64:67]
	s_setprio 0
	s_barrier
; #define LAS __attribute__((address_space(3)))
; #define PG8_STAGE(bufoff, gbase, voff) do { _Pragma("unroll") for (int _i = 0; _i < 2; ++_i) \
;         __builtin_amdgcn_global_load_lds((const unsigned*)((const char*)(gbase) + (voff)[_i]), (LAS unsigned*)(lds + (bufoff) + ldsw + _i * 8192), 16, 0, 0); } while (0)
; #define PG8_LDA(dst, b, h) do { _Pragma("unroll") for (int m = 0; m < 4; ++m) _Pragma("unroll") for (int k = 0; k < 2; ++k) dst[m][k] = *(const LAS bf16x8*)(lds + PG8_SA(b, h) + aoff + m * 2048 + k * 1024); } while (0)
; #define PG8_LDB(dst, b, h) do { _Pragma("unroll") for (int n = 0; n < 2; ++n) _Pragma("unroll") for (int k = 0; k < 2; ++k) dst[n][k] = *(const LAS bf16x8*)(lds + PG8_SB(b, h) + boff + n * 2048 + k * 1024); } while (0)
; #define PG8_WAIT_V(n) asm volatile("s_waitcnt vmcnt(" #n ")" ::: "memory")
; #define PG8_WAIT_L(n) asm volatile("s_waitcnt lgkmcnt(" #n ")" ::: "memory")
; template <class Epi, class Sched>
; __device__ __forceinline__ void gemm_phase(LAS unsigned char* lds, const int K, const int lda, const int ldb, const Sched& S, const Epi& E) {
;     ...
;             PG8_LDB(B0, 1, 0); PG8_LDB(B1, 1, 1); PG8_SCHED; PG8_LDA(At, 1, 0); PG8_STAGE(PG8_SA(0, 1), a2 + hA, voffA);
;             PG8_WAIT_V(8); PG8_WAIT_L(0); PG8_BAR; PG8_MMA(0, 0, At, B0); PG8_MMA(0, 1, At, B1); PG8_BAR; PG8_SCHED;
;             PG8_LDA(At, 1, 1); PG8_STAGE(PG8_SB(1, 0), b3, voffB); PG8_STAGE(PG8_SB(1, 1), b3 + hB, voffB); PG8_STAGE(PG8_SA(1, 0), a3, voffA);
;             PG8_WAIT_V(8); PG8_WAIT_L(0); PG8_BAR; PG8_MMA(1, 0, At, B0); PG8_MMA(1, 1, At, B1); PG8_BAR; PG8_SCHED;
;         }
;         if (wr == 0) PG8_BAR;
;     __device__ __forceinline__ void operator()(const f32x4 (&acc)[2][2][4][2], const Unit& u, int wr, int wc, int fr, int fq, LAS unsigned char* xs, int wid, int lane) const {
;         const int row0 = u.pm * 256 + wr * 64, col0 = u.pn * 256 + wc * 32 + 8 * fq;
;         const float* xo = (row0 < TP) ? xo_p : xo_s - (size_t)TP * D;
;         LAS float* P = (LAS float*)xs;
;         u32x4 raw[2][4][2];
;         if (!SRCF32) {
; #pragma unroll
;             for (int ai = 0; ai < 2; ++ai)
; #pragma unroll
;                 for (int m = 0; m < 4; ++m)
; #pragma unroll
;                     for (int bj = 0; bj < 2; ++bj) raw[ai][m][bj] = *(const u32x4*)(xb + (size_t)(row0 + ai * 128 + m * 16 + fr) * D + col0 + bj * 128);
	s_add_i32 s34, s52, s36
	v_lshl_add_u64 v[192:193], v[192:193], 0, s[10:11]
	s_mov_b32 m0, s34
	ds_read_b128 v[160:163], v199 offset:49152
	ds_read_b128 v[180:183], v199 offset:50176
	ds_read_b128 v[184:187], v199 offset:51200
	ds_read_b128 v[188:191], v199 offset:52224
	ds_read_b128 v[200:203], v199 offset:53248
	ds_read_b128 v[204:207], v199 offset:54272
	ds_read_b128 v[208:211], v199 offset:55296
	ds_read_b128 v[212:215], v199 offset:56320
	global_load_lds_dwordx4 v[192:193], off
	s_add_i32 m0, s34, 0x2000
	s_add_u32 s30, s30, 0x80080
	v_lshl_add_u64 v[192:193], v[216:217], 0, s[10:11]
	s_addc_u32 s31, s31, 0
	s_add_i32 s34, s53, s36
	global_load_lds_dwordx4 v[192:193], off
	v_lshl_add_u64 v[192:193], s[30:31], 0, v[166:167]
	s_mov_b32 m0, s34
	s_nop 0
	global_load_lds_dwordx4 v[192:193], off
	v_lshl_add_u64 v[192:193], s[30:31], 0, v[170:171]
	s_add_i32 m0, s34, 0x2000
	s_nop 0
	global_load_lds_dwordx4 v[192:193], off
	v_lshl_add_u64 v[192:193], v[218:219], 0, s[10:11]
	s_mov_b32 m0, s41
	s_nop 0
	global_load_lds_dwordx4 v[192:193], off
	v_lshl_add_u64 v[192:193], v[220:221], 0, s[10:11]
	s_mov_b32 m0, s42
	s_nop 0
	global_load_lds_dwordx4 v[192:193], off
	s_waitcnt vmcnt(8)
	s_waitcnt lgkmcnt(0)
	s_barrier
	s_setprio 1
	s_waitcnt lgkmcnt(0)
	v_mfma_f32_16x16x32_bf16 v[60:63], v[160:163], v[128:131], v[60:63]
	v_mfma_f32_16x16x32_bf16 v[56:59], v[160:163], v[136:139], v[56:59]
	v_mfma_f32_16x16x32_bf16 v[48:51], v[184:187], v[128:131], v[48:51]
	v_mfma_f32_16x16x32_bf16 v[40:43], v[184:187], v[136:139], v[40:43]
	v_mfma_f32_16x16x32_bf16 v[32:35], v[200:203], v[128:131], v[32:35]
	v_mfma_f32_16x16x32_bf16 v[24:27], v[200:203], v[136:139], v[24:27]
	v_mfma_f32_16x16x32_bf16 v[16:19], v[208:211], v[128:131], v[16:19]
	v_mfma_f32_16x16x32_bf16 v[8:11], v[208:211], v[136:139], v[8:11]
	v_mfma_f32_16x16x32_bf16 v[60:63], v[180:183], v[132:135], v[60:63]
	v_mfma_f32_16x16x32_bf16 v[56:59], v[180:183], v[140:143], v[56:59]
	v_mfma_f32_16x16x32_bf16 v[48:51], v[188:191], v[132:135], v[48:51]
	v_mfma_f32_16x16x32_bf16 v[40:43], v[188:191], v[140:143], v[40:43]
	v_mfma_f32_16x16x32_bf16 v[32:35], v[204:207], v[132:135], v[32:35]
	v_mfma_f32_16x16x32_bf16 v[24:27], v[204:207], v[140:143], v[24:27]
	v_mfma_f32_16x16x32_bf16 v[16:19], v[212:215], v[132:135], v[16:19]
	v_mfma_f32_16x16x32_bf16 v[8:11], v[212:215], v[140:143], v[8:11]
	s_setprio 0
	s_setprio 1
	v_mfma_f32_16x16x32_bf16 v[52:55], v[160:163], v[144:147], v[52:55]
	v_mfma_f32_16x16x32_bf16 v[44:47], v[160:163], v[152:155], v[44:47]
	v_mfma_f32_16x16x32_bf16 v[36:39], v[184:187], v[144:147], v[36:39]
	v_mfma_f32_16x16x32_bf16 v[28:31], v[184:187], v[152:155], v[28:31]
	v_mfma_f32_16x16x32_bf16 v[20:23], v[200:203], v[144:147], v[20:23]
	v_mfma_f32_16x16x32_bf16 v[12:15], v[200:203], v[152:155], v[12:15]
	v_mfma_f32_16x16x32_bf16 v[4:7], v[208:211], v[144:147], v[4:7]
	v_mfma_f32_16x16x32_bf16 v[0:3], v[208:211], v[152:155], v[0:3]
	v_mfma_f32_16x16x32_bf16 v[52:55], v[180:183], v[148:151], v[52:55]
	v_mfma_f32_16x16x32_bf16 v[44:47], v[180:183], v[156:159], v[44:47]
	v_mfma_f32_16x16x32_bf16 v[36:39], v[188:191], v[148:151], v[36:39]
	v_mfma_f32_16x16x32_bf16 v[28:31], v[188:191], v[156:159], v[28:31]
	v_mfma_f32_16x16x32_bf16 v[20:23], v[204:207], v[148:151], v[20:23]
	v_mfma_f32_16x16x32_bf16 v[12:15], v[204:207], v[156:159], v[12:15]
	v_mfma_f32_16x16x32_bf16 v[4:7], v[212:215], v[148:151], v[4:7]
	v_mfma_f32_16x16x32_bf16 v[0:3], v[212:215], v[156:159], v[0:3]
	s_setprio 0
	s_barrier
	s_add_i32 s51, s51, 2
	s_add_u32 s49, s49, 0x100
	s_addc_u32 s50, s50, 0
	s_add_u32 s28, s28, 0x100
	s_addc_u32 s29, s29, 0
	s_cmp_gt_u32 s51, 29
	s_cbranch_scc0 .LBB0_1625
	s_and_b64 vcc, exec, s[14:15]
	s_cbranch_vccz .LBB0_1628
	s_barrier
.LBB0_1628:
	v_readfirstlane_b32 s52, v254
	s_nop 1
	s_lshr_b32 s52, s52, 6
	s_lshr_b32 s53, s52, 2
	s_and_b32 s52, s52, 3
	s_lshl_b32 s54, s26, 8
	s_lshl_b32 s53, s53, 6
	s_add_i32 s54, s54, s53
	s_lshl_b32 s55, s46, 8
	s_lshl_b32 s52, s52, 6
	s_add_i32 s55, s55, s52
	s_lshl_b32 s54, s54, 11
	s_add_i32 s54, s54, s55
	s_lshl_b32 s55, s54, 1
	s_add_u32 s56, s16, s55
	s_addc_u32 s57, s17, 0
	s_lshl_b32 s55, s54, 2
	s_add_u32 s58, s4, s55
	s_addc_u32 s59, s5, 0
	v_and_b32_e32 v246, 15, v254
	v_bfe_u32 v247, v254, 4, 2
	v_lshlrev_b32_e32 v245, 13, v247
	v_lshl_add_u32 v245, v246, 2, v245
	v_lshlrev_b32_e32 v244, 1, v245
	v_lshlrev_b32_e32 v245, 2, v245
	s_add_u32 s60, s56, 0x0
	s_addc_u32 s61, s57, 0
	global_load_dwordx2 v[128:129], v244, s[60:61]
	s_add_u32 s62, s56, 0x1000
	s_addc_u32 s63, s57, 0
	global_load_dwordx2 v[130:131], v244, s[62:63]
	s_add_u32 s60, s56, 0x2000
	s_addc_u32 s61, s57, 0
	global_load_dwordx2 v[132:133], v244, s[60:61]
	s_add_u32 s62, s56, 0x3000
	s_addc_u32 s63, s57, 0
	global_load_dwordx2 v[134:135], v244, s[62:63]
	s_add_u32 s60, s56, 0x10000
	s_addc_u32 s61, s57, 0
	global_load_dwordx2 v[136:137], v244, s[60:61]
	s_add_u32 s62, s56, 0x11000
	s_addc_u32 s63, s57, 0
	global_load_dwordx2 v[138:139], v244, s[62:63]
	s_add_u32 s60, s56, 0x12000
	s_addc_u32 s61, s57, 0
	global_load_dwordx2 v[140:141], v244, s[60:61]
	s_add_u32 s62, s56, 0x13000
	s_addc_u32 s63, s57, 0
	global_load_dwordx2 v[142:143], v244, s[62:63]
	s_add_u32 s60, s56, 0x20000
	s_addc_u32 s61, s57, 0
	global_load_dwordx2 v[144:145], v244, s[60:61]
	s_add_u32 s62, s56, 0x21000
	s_addc_u32 s63, s57, 0
	global_load_dwordx2 v[146:147], v244, s[62:63]
	s_add_u32 s60, s56, 0x22000
	s_addc_u32 s61, s57, 0
	global_load_dwordx2 v[148:149], v244, s[60:61]
	s_add_u32 s62, s56, 0x23000
	s_addc_u32 s63, s57, 0
	global_load_dwordx2 v[150:151], v244, s[62:63]
	s_add_u32 s60, s56, 0x30000
;     __device__ __forceinline__ void operator()(const f32x4 (&acc)[2][2][4][2], const Unit& u, int wr, int wc, int fr, int fq, LAS unsigned char* xs, int wid, int lane) const {
;     ...
; #pragma unroll
;             for (int m = 0; m < 4; ++m) {
;                 const size_t row = (size_t)(row0 + ai * 128 + m * 16 + fr);
;                 float ss = 0.f;
; #pragma unroll
;                 for (int bj = 0; bj < 2; ++bj) {
;                     const size_t o = row * D + col0 + bj * 128;
;                     f32x4 x0, x1;
;                     if (SRCF32) { x0 = xf[m][bj][0]; x1 = xf[m][bj][1]; }
;                     else { const u32x4 r = raw[ai][m][bj]; x0 = (f32x4){bf_lo(r.x), bf_hi(r.x), bf_lo(r.y), bf_hi(r.y)}; x1 = (f32x4){bf_lo(r.z), bf_hi(r.z), bf_lo(r.w), bf_hi(r.w)}; }
;                     const f32x4 v0 = x0 + acc[ai][bj][m][0], v1 = x1 + acc[ai][bj][m][1];
;                     if (LAST) { *(f32x4*)(out + o) = v0; *(f32x4*)(out + o + 4) = v1; }
	s_addc_u32 s61, s57, 0
	global_load_dwordx2 v[152:153], v244, s[60:61]
	s_add_u32 s62, s56, 0x31000
	s_addc_u32 s63, s57, 0
	global_load_dwordx2 v[154:155], v244, s[62:63]
	s_add_u32 s60, s56, 0x32000
	s_addc_u32 s61, s57, 0
	global_load_dwordx2 v[156:157], v244, s[60:61]
	s_add_u32 s62, s56, 0x33000
	s_addc_u32 s63, s57, 0
	global_load_dwordx2 v[158:159], v244, s[62:63]
	s_add_u32 s60, s56, 0x80000
	s_addc_u32 s61, s57, 0
	global_load_dwordx2 v[160:161], v244, s[60:61]
	s_add_u32 s62, s56, 0x81000
	s_addc_u32 s63, s57, 0
	global_load_dwordx2 v[162:163], v244, s[62:63]
	s_add_u32 s60, s56, 0x82000
	s_addc_u32 s61, s57, 0
	global_load_dwordx2 v[200:201], v244, s[60:61]
	s_add_u32 s62, s56, 0x83000
	s_addc_u32 s63, s57, 0
	global_load_dwordx2 v[202:203], v244, s[62:63]
	s_add_u32 s60, s56, 0x90000
	s_addc_u32 s61, s57, 0
	global_load_dwordx2 v[204:205], v244, s[60:61]
	s_add_u32 s62, s56, 0x91000
	s_addc_u32 s63, s57, 0
	global_load_dwordx2 v[206:207], v244, s[62:63]
	s_add_u32 s60, s56, 0x92000
	s_addc_u32 s61, s57, 0
	global_load_dwordx2 v[208:209], v244, s[60:61]
	s_add_u32 s62, s56, 0x93000
	s_addc_u32 s63, s57, 0
	global_load_dwordx2 v[210:211], v244, s[62:63]
	s_add_u32 s60, s56, 0xa0000
	s_addc_u32 s61, s57, 0
	global_load_dwordx2 v[212:213], v244, s[60:61]
	s_add_u32 s62, s56, 0xa1000
	s_addc_u32 s63, s57, 0
	global_load_dwordx2 v[214:215], v244, s[62:63]
	s_add_u32 s60, s56, 0xa2000
	s_addc_u32 s61, s57, 0
	global_load_dwordx2 v[216:217], v244, s[60:61]
	s_add_u32 s62, s56, 0xa3000
	s_addc_u32 s63, s57, 0
	global_load_dwordx2 v[218:219], v244, s[62:63]
	s_add_u32 s60, s56, 0xb0000
	s_addc_u32 s61, s57, 0
	global_load_dwordx2 v[220:221], v244, s[60:61]
	s_add_u32 s62, s56, 0xb1000
	s_addc_u32 s63, s57, 0
	global_load_dwordx2 v[222:223], v244, s[62:63]
	s_add_u32 s60, s56, 0xb2000
	s_addc_u32 s61, s57, 0
	global_load_dwordx2 v[224:225], v244, s[60:61]
	s_add_u32 s62, s56, 0xb3000
	s_addc_u32 s63, s57, 0
	global_load_dwordx2 v[226:227], v244, s[62:63]
	s_waitcnt vmcnt(31)
	v_lshlrev_b32_e32 v248, 16, v128
	v_and_b32_e32 v249, 0xffff0000, v128
	v_add_f32_e32 v228, v124, v248
	v_add_f32_e32 v229, v120, v249
	v_lshlrev_b32_e32 v248, 16, v129
	v_and_b32_e32 v249, 0xffff0000, v129
	v_add_f32_e32 v230, v116, v248
	v_add_f32_e32 v231, v112, v249
	s_add_u32 s60, s58, 0x0
	s_addc_u32 s61, s59, 0
	global_store_dwordx4 v245, v[228:231], s[60:61]
	s_waitcnt vmcnt(31)
	v_lshlrev_b32_e32 v248, 16, v130
	v_and_b32_e32 v249, 0xffff0000, v130
	v_add_f32_e32 v232, v125, v248
	v_add_f32_e32 v233, v121, v249
	v_lshlrev_b32_e32 v248, 16, v131
	v_and_b32_e32 v249, 0xffff0000, v131
	v_add_f32_e32 v234, v117, v248
	v_add_f32_e32 v235, v113, v249
	s_add_u32 s62, s58, 0x2000
	s_addc_u32 s63, s59, 0
	global_store_dwordx4 v245, v[232:235], s[62:63]
	s_waitcnt vmcnt(31)
	v_lshlrev_b32_e32 v248, 16, v132
	v_and_b32_e32 v249, 0xffff0000, v132
	v_add_f32_e32 v236, v126, v248
	v_add_f32_e32 v237, v122, v249
	v_lshlrev_b32_e32 v248, 16, v133
	v_and_b32_e32 v249, 0xffff0000, v133
	v_add_f32_e32 v238, v118, v248
	v_add_f32_e32 v239, v114, v249
	s_add_u32 s60, s58, 0x4000
	s_addc_u32 s61, s59, 0
	global_store_dwordx4 v245, v[236:239], s[60:61]
	s_waitcnt vmcnt(31)
	v_lshlrev_b32_e32 v248, 16, v134
	v_and_b32_e32 v249, 0xffff0000, v134
	v_add_f32_e32 v240, v127, v248
	v_add_f32_e32 v241, v123, v249
	v_lshlrev_b32_e32 v248, 16, v135
	v_and_b32_e32 v249, 0xffff0000, v135
	v_add_f32_e32 v242, v119, v248
	v_add_f32_e32 v243, v115, v249
	s_add_u32 s62, s58, 0x6000
	s_addc_u32 s63, s59, 0
	global_store_dwordx4 v245, v[240:243], s[62:63]
	s_waitcnt vmcnt(31)
	v_lshlrev_b32_e32 v248, 16, v136
	v_and_b32_e32 v249, 0xffff0000, v136
	v_add_f32_e32 v228, v108, v248
	v_add_f32_e32 v229, v104, v249
	v_lshlrev_b32_e32 v248, 16, v137
	v_and_b32_e32 v249, 0xffff0000, v137
	v_add_f32_e32 v230, v100, v248
	v_add_f32_e32 v231, v92, v249
	s_add_u32 s60, s58, 0x20000
	s_addc_u32 s61, s59, 0
	global_store_dwordx4 v245, v[228:231], s[60:61]
	s_waitcnt vmcnt(31)
	v_lshlrev_b32_e32 v248, 16, v138
	v_and_b32_e32 v249, 0xffff0000, v138
	v_add_f32_e32 v232, v109, v248
	v_add_f32_e32 v233, v105, v249
	v_lshlrev_b32_e32 v248, 16, v139
	v_and_b32_e32 v249, 0xffff0000, v139
	v_add_f32_e32 v234, v101, v248
	v_add_f32_e32 v235, v93, v249
	s_add_u32 s62, s58, 0x22000
	s_addc_u32 s63, s59, 0
	global_store_dwordx4 v245, v[232:235], s[62:63]
	s_waitcnt vmcnt(31)
	v_lshlrev_b32_e32 v248, 16, v140
	v_and_b32_e32 v249, 0xffff0000, v140
	v_add_f32_e32 v236, v110, v248
	v_add_f32_e32 v237, v106, v249
	v_lshlrev_b32_e32 v248, 16, v141
	v_and_b32_e32 v249, 0xffff0000, v141
	v_add_f32_e32 v238, v102, v248
	v_add_f32_e32 v239, v94, v249
	s_add_u32 s60, s58, 0x24000
	s_addc_u32 s61, s59, 0
	global_store_dwordx4 v245, v[236:239], s[60:61]
	s_waitcnt vmcnt(31)
	v_lshlrev_b32_e32 v248, 16, v142
	v_and_b32_e32 v249, 0xffff0000, v142
	v_add_f32_e32 v240, v111, v248
	v_add_f32_e32 v241, v107, v249
	v_lshlrev_b32_e32 v248, 16, v143
	v_and_b32_e32 v249, 0xffff0000, v143
	v_add_f32_e32 v242, v103, v248
	v_add_f32_e32 v243, v95, v249
	s_add_u32 s62, s58, 0x26000
	s_addc_u32 s63, s59, 0
	global_store_dwordx4 v245, v[240:243], s[62:63]
	s_waitcnt vmcnt(31)
	v_lshlrev_b32_e32 v248, 16, v144
	v_and_b32_e32 v249, 0xffff0000, v144
	v_add_f32_e32 v228, v96, v248
	v_add_f32_e32 v229, v88, v249
	v_lshlrev_b32_e32 v248, 16, v145
	v_and_b32_e32 v249, 0xffff0000, v145
	v_add_f32_e32 v230, v84, v248
	v_add_f32_e32 v231, v76, v249
	s_add_u32 s60, s58, 0x40000
	s_addc_u32 s61, s59, 0
	global_store_dwordx4 v245, v[228:231], s[60:61]
	s_waitcnt vmcnt(31)
;     __device__ __forceinline__ void operator()(const f32x4 (&acc)[2][2][4][2], const Unit& u, int wr, int wc, int fr, int fq, LAS unsigned char* xs, int wid, int lane) const {
;     ...
; #pragma unroll
;             for (int m = 0; m < 4; ++m) {
;                 const size_t row = (size_t)(row0 + ai * 128 + m * 16 + fr);
;                 float ss = 0.f;
; #pragma unroll
;                 for (int bj = 0; bj < 2; ++bj) {
;                     const size_t o = row * D + col0 + bj * 128;
;                     f32x4 x0, x1;
;                     if (SRCF32) { x0 = xf[m][bj][0]; x1 = xf[m][bj][1]; }
;                     else { const u32x4 r = raw[ai][m][bj]; x0 = (f32x4){bf_lo(r.x), bf_hi(r.x), bf_lo(r.y), bf_hi(r.y)}; x1 = (f32x4){bf_lo(r.z), bf_hi(r.z), bf_lo(r.w), bf_hi(r.w)}; }
;                     const f32x4 v0 = x0 + acc[ai][bj][m][0], v1 = x1 + acc[ai][bj][m][1];
;                     if (LAST) { *(f32x4*)(out + o) = v0; *(f32x4*)(out + o + 4) = v1; }
	v_lshlrev_b32_e32 v248, 16, v146
	v_and_b32_e32 v249, 0xffff0000, v146
	v_add_f32_e32 v232, v97, v248
	v_add_f32_e32 v233, v89, v249
	v_lshlrev_b32_e32 v248, 16, v147
	v_and_b32_e32 v249, 0xffff0000, v147
	v_add_f32_e32 v234, v85, v248
	v_add_f32_e32 v235, v77, v249
	s_add_u32 s62, s58, 0x42000
	s_addc_u32 s63, s59, 0
	global_store_dwordx4 v245, v[232:235], s[62:63]
	s_waitcnt vmcnt(31)
	v_lshlrev_b32_e32 v248, 16, v148
	v_and_b32_e32 v249, 0xffff0000, v148
	v_add_f32_e32 v236, v98, v248
	v_add_f32_e32 v237, v90, v249
	v_lshlrev_b32_e32 v248, 16, v149
	v_and_b32_e32 v249, 0xffff0000, v149
	v_add_f32_e32 v238, v86, v248
	v_add_f32_e32 v239, v78, v249
	s_add_u32 s60, s58, 0x44000
	s_addc_u32 s61, s59, 0
	global_store_dwordx4 v245, v[236:239], s[60:61]
	s_waitcnt vmcnt(31)
	v_lshlrev_b32_e32 v248, 16, v150
	v_and_b32_e32 v249, 0xffff0000, v150
	v_add_f32_e32 v240, v99, v248
	v_add_f32_e32 v241, v91, v249
	v_lshlrev_b32_e32 v248, 16, v151
	v_and_b32_e32 v249, 0xffff0000, v151
	v_add_f32_e32 v242, v87, v248
	v_add_f32_e32 v243, v79, v249
	s_add_u32 s62, s58, 0x46000
	s_addc_u32 s63, s59, 0
	global_store_dwordx4 v245, v[240:243], s[62:63]
	s_waitcnt vmcnt(31)
	v_lshlrev_b32_e32 v248, 16, v152
	v_and_b32_e32 v249, 0xffff0000, v152
	v_add_f32_e32 v228, v80, v248
	v_add_f32_e32 v229, v72, v249
	v_lshlrev_b32_e32 v248, 16, v153
	v_and_b32_e32 v249, 0xffff0000, v153
	v_add_f32_e32 v230, v68, v248
	v_add_f32_e32 v231, v64, v249
	s_add_u32 s60, s58, 0x60000
	s_addc_u32 s61, s59, 0
	global_store_dwordx4 v245, v[228:231], s[60:61]
	s_waitcnt vmcnt(31)
	v_lshlrev_b32_e32 v248, 16, v154
	v_and_b32_e32 v249, 0xffff0000, v154
	v_add_f32_e32 v232, v81, v248
	v_add_f32_e32 v233, v73, v249
	v_lshlrev_b32_e32 v248, 16, v155
	v_and_b32_e32 v249, 0xffff0000, v155
	v_add_f32_e32 v234, v69, v248
	v_add_f32_e32 v235, v65, v249
	s_add_u32 s62, s58, 0x62000
	s_addc_u32 s63, s59, 0
	global_store_dwordx4 v245, v[232:235], s[62:63]
	s_waitcnt vmcnt(31)
	v_lshlrev_b32_e32 v248, 16, v156
	v_and_b32_e32 v249, 0xffff0000, v156
	v_add_f32_e32 v236, v82, v248
	v_add_f32_e32 v237, v74, v249
	v_lshlrev_b32_e32 v248, 16, v157
	v_and_b32_e32 v249, 0xffff0000, v157
	v_add_f32_e32 v238, v70, v248
	v_add_f32_e32 v239, v66, v249
	s_add_u32 s60, s58, 0x64000
	s_addc_u32 s61, s59, 0
	global_store_dwordx4 v245, v[236:239], s[60:61]
	s_waitcnt vmcnt(31)
	v_lshlrev_b32_e32 v248, 16, v158
	v_and_b32_e32 v249, 0xffff0000, v158
	v_add_f32_e32 v240, v83, v248
	v_add_f32_e32 v241, v75, v249
	v_lshlrev_b32_e32 v248, 16, v159
	v_and_b32_e32 v249, 0xffff0000, v159
	v_add_f32_e32 v242, v71, v248
	v_add_f32_e32 v243, v67, v249
	s_add_u32 s62, s58, 0x66000
	s_addc_u32 s63, s59, 0
	global_store_dwordx4 v245, v[240:243], s[62:63]
	s_waitcnt vmcnt(31)
	v_lshlrev_b32_e32 v248, 16, v160
	v_and_b32_e32 v249, 0xffff0000, v160
	v_add_f32_e32 v228, v60, v248
	v_add_f32_e32 v229, v56, v249
	v_lshlrev_b32_e32 v248, 16, v161
	v_and_b32_e32 v249, 0xffff0000, v161
	v_add_f32_e32 v230, v52, v248
	v_add_f32_e32 v231, v44, v249
	s_add_u32 s60, s58, 0x100000
	s_addc_u32 s61, s59, 0
	global_store_dwordx4 v245, v[228:231], s[60:61]
	s_waitcnt vmcnt(31)
	v_lshlrev_b32_e32 v248, 16, v162
	v_and_b32_e32 v249, 0xffff0000, v162
	v_add_f32_e32 v232, v61, v248
	v_add_f32_e32 v233, v57, v249
	v_lshlrev_b32_e32 v248, 16, v163
	v_and_b32_e32 v249, 0xffff0000, v163
	v_add_f32_e32 v234, v53, v248
	v_add_f32_e32 v235, v45, v249
	s_add_u32 s62, s58, 0x102000
	s_addc_u32 s63, s59, 0
	global_store_dwordx4 v245, v[232:235], s[62:63]
	s_waitcnt vmcnt(31)
	v_lshlrev_b32_e32 v248, 16, v200
	v_and_b32_e32 v249, 0xffff0000, v200
	v_add_f32_e32 v236, v62, v248
	v_add_f32_e32 v237, v58, v249
	v_lshlrev_b32_e32 v248, 16, v201
	v_and_b32_e32 v249, 0xffff0000, v201
	v_add_f32_e32 v238, v54, v248
	v_add_f32_e32 v239, v46, v249
	s_add_u32 s60, s58, 0x104000
	s_addc_u32 s61, s59, 0
	global_store_dwordx4 v245, v[236:239], s[60:61]
	s_waitcnt vmcnt(31)
	v_lshlrev_b32_e32 v248, 16, v202
	v_and_b32_e32 v249, 0xffff0000, v202
	v_add_f32_e32 v240, v63, v248
	v_add_f32_e32 v241, v59, v249
	v_lshlrev_b32_e32 v248, 16, v203
	v_and_b32_e32 v249, 0xffff0000, v203
	v_add_f32_e32 v242, v55, v248
	v_add_f32_e32 v243, v47, v249
	s_add_u32 s62, s58, 0x106000
	s_addc_u32 s63, s59, 0
	global_store_dwordx4 v245, v[240:243], s[62:63]
	s_waitcnt vmcnt(31)
	v_lshlrev_b32_e32 v248, 16, v204
	v_and_b32_e32 v249, 0xffff0000, v204
	v_add_f32_e32 v228, v48, v248
	v_add_f32_e32 v229, v40, v249
	v_lshlrev_b32_e32 v248, 16, v205
	v_and_b32_e32 v249, 0xffff0000, v205
	v_add_f32_e32 v230, v36, v248
	v_add_f32_e32 v231, v28, v249
	s_add_u32 s60, s58, 0x120000
	s_addc_u32 s61, s59, 0
	global_store_dwordx4 v245, v[228:231], s[60:61]
	s_waitcnt vmcnt(31)
; #define PG8_BAR __builtin_amdgcn_s_barrier()
; template <class Epi, class Sched>
; __device__ __forceinline__ void gemm_phase(LAS unsigned char* lds, const int K, const int lda, const int ldb, const Sched& S, const Epi& E) {
;     ...
;         if (!has_next) break;
; #pragma unroll
;         for (int a = 0; a < 2; ++a)
; #pragma unroll
;             for (int b = 0; b < 2; ++b)
; #pragma unroll
;                 for (int m = 0; m < 4; ++m)
; #pragma unroll
;                     for (int n = 0; n < 2; ++n) acc[a][b][m][n] = (f32x4){0.f, 0.f, 0.f, 0.f};
;         cur = nxt; cA = nA; cB = nB; ++ui;
;         if (wr == 1) PG8_BAR;
;     }
;     __device__ __forceinline__ void operator()(const f32x4 (&acc)[2][2][4][2], const Unit& u, int wr, int wc, int fr, int fq, LAS unsigned char* xs, int wid, int lane) const {
;     ...
; #pragma unroll
;             for (int m = 0; m < 4; ++m) {
;                 const size_t row = (size_t)(row0 + ai * 128 + m * 16 + fr);
;                 float ss = 0.f;
; #pragma unroll
;                 for (int bj = 0; bj < 2; ++bj) {
;                     const size_t o = row * D + col0 + bj * 128;
;                     f32x4 x0, x1;
;                     if (SRCF32) { x0 = xf[m][bj][0]; x1 = xf[m][bj][1]; }
;                     else { const u32x4 r = raw[ai][m][bj]; x0 = (f32x4){bf_lo(r.x), bf_hi(r.x), bf_lo(r.y), bf_hi(r.y)}; x1 = (f32x4){bf_lo(r.z), bf_hi(r.z), bf_lo(r.w), bf_hi(r.w)}; }
;                     const f32x4 v0 = x0 + acc[ai][bj][m][0], v1 = x1 + acc[ai][bj][m][1];
;                     if (LAST) { *(f32x4*)(out + o) = v0; *(f32x4*)(out + o + 4) = v1; }
	v_lshlrev_b32_e32 v248, 16, v206
	v_and_b32_e32 v249, 0xffff0000, v206
	v_add_f32_e32 v232, v49, v248
	v_add_f32_e32 v233, v41, v249
	v_lshlrev_b32_e32 v248, 16, v207
	v_and_b32_e32 v249, 0xffff0000, v207
	v_add_f32_e32 v234, v37, v248
	v_add_f32_e32 v235, v29, v249
	s_add_u32 s62, s58, 0x122000
	s_addc_u32 s63, s59, 0
	global_store_dwordx4 v245, v[232:235], s[62:63]
	s_waitcnt vmcnt(31)
	v_lshlrev_b32_e32 v248, 16, v208
	v_and_b32_e32 v249, 0xffff0000, v208
	v_add_f32_e32 v236, v50, v248
	v_add_f32_e32 v237, v42, v249
	v_lshlrev_b32_e32 v248, 16, v209
	v_and_b32_e32 v249, 0xffff0000, v209
	v_add_f32_e32 v238, v38, v248
	v_add_f32_e32 v239, v30, v249
	s_add_u32 s60, s58, 0x124000
	s_addc_u32 s61, s59, 0
	global_store_dwordx4 v245, v[236:239], s[60:61]
	s_waitcnt vmcnt(31)
	v_lshlrev_b32_e32 v248, 16, v210
	v_and_b32_e32 v249, 0xffff0000, v210
	v_add_f32_e32 v240, v51, v248
	v_add_f32_e32 v241, v43, v249
	v_lshlrev_b32_e32 v248, 16, v211
	v_and_b32_e32 v249, 0xffff0000, v211
	v_add_f32_e32 v242, v39, v248
	v_add_f32_e32 v243, v31, v249
	s_add_u32 s62, s58, 0x126000
	s_addc_u32 s63, s59, 0
	global_store_dwordx4 v245, v[240:243], s[62:63]
	s_waitcnt vmcnt(31)
	v_lshlrev_b32_e32 v248, 16, v212
	v_and_b32_e32 v249, 0xffff0000, v212
	v_add_f32_e32 v228, v32, v248
	v_add_f32_e32 v229, v24, v249
	v_lshlrev_b32_e32 v248, 16, v213
	v_and_b32_e32 v249, 0xffff0000, v213
	v_add_f32_e32 v230, v20, v248
	v_add_f32_e32 v231, v12, v249
	s_add_u32 s60, s58, 0x140000
	s_addc_u32 s61, s59, 0
	global_store_dwordx4 v245, v[228:231], s[60:61]
	s_waitcnt vmcnt(31)
	v_lshlrev_b32_e32 v248, 16, v214
	v_and_b32_e32 v249, 0xffff0000, v214
	v_add_f32_e32 v232, v33, v248
	v_add_f32_e32 v233, v25, v249
	v_lshlrev_b32_e32 v248, 16, v215
	v_and_b32_e32 v249, 0xffff0000, v215
	v_add_f32_e32 v234, v21, v248
	v_add_f32_e32 v235, v13, v249
	s_add_u32 s62, s58, 0x142000
	s_addc_u32 s63, s59, 0
	global_store_dwordx4 v245, v[232:235], s[62:63]
	s_waitcnt vmcnt(31)
	v_lshlrev_b32_e32 v248, 16, v216
	v_and_b32_e32 v249, 0xffff0000, v216
	v_add_f32_e32 v236, v34, v248
	v_add_f32_e32 v237, v26, v249
	v_lshlrev_b32_e32 v248, 16, v217
	v_and_b32_e32 v249, 0xffff0000, v217
	v_add_f32_e32 v238, v22, v248
	v_add_f32_e32 v239, v14, v249
	s_add_u32 s60, s58, 0x144000
	s_addc_u32 s61, s59, 0
	global_store_dwordx4 v245, v[236:239], s[60:61]
	s_waitcnt vmcnt(31)
	v_lshlrev_b32_e32 v248, 16, v218
	v_and_b32_e32 v249, 0xffff0000, v218
	v_add_f32_e32 v240, v35, v248
	v_add_f32_e32 v241, v27, v249
	v_lshlrev_b32_e32 v248, 16, v219
	v_and_b32_e32 v249, 0xffff0000, v219
	v_add_f32_e32 v242, v23, v248
	v_add_f32_e32 v243, v15, v249
	s_add_u32 s62, s58, 0x146000
	s_addc_u32 s63, s59, 0
	global_store_dwordx4 v245, v[240:243], s[62:63]
	s_waitcnt vmcnt(31)
	v_lshlrev_b32_e32 v248, 16, v220
	v_and_b32_e32 v249, 0xffff0000, v220
	v_add_f32_e32 v228, v16, v248
	v_add_f32_e32 v229, v8, v249
	v_lshlrev_b32_e32 v248, 16, v221
	v_and_b32_e32 v249, 0xffff0000, v221
	v_add_f32_e32 v230, v4, v248
	v_add_f32_e32 v231, v0, v249
	s_add_u32 s60, s58, 0x160000
	s_addc_u32 s61, s59, 0
	global_store_dwordx4 v245, v[228:231], s[60:61]
	s_waitcnt vmcnt(31)
	v_lshlrev_b32_e32 v248, 16, v222
	v_and_b32_e32 v249, 0xffff0000, v222
	v_add_f32_e32 v232, v17, v248
	v_add_f32_e32 v233, v9, v249
	v_lshlrev_b32_e32 v248, 16, v223
	v_and_b32_e32 v249, 0xffff0000, v223
	v_add_f32_e32 v234, v5, v248
	v_add_f32_e32 v235, v1, v249
	s_add_u32 s62, s58, 0x162000
	s_addc_u32 s63, s59, 0
	global_store_dwordx4 v245, v[232:235], s[62:63]
	s_waitcnt vmcnt(31)
	v_lshlrev_b32_e32 v248, 16, v224
	v_and_b32_e32 v249, 0xffff0000, v224
	v_add_f32_e32 v236, v18, v248
	v_add_f32_e32 v237, v10, v249
	v_lshlrev_b32_e32 v248, 16, v225
	v_and_b32_e32 v249, 0xffff0000, v225
	v_add_f32_e32 v238, v6, v248
	v_add_f32_e32 v239, v2, v249
	s_add_u32 s60, s58, 0x164000
	s_addc_u32 s61, s59, 0
	global_store_dwordx4 v245, v[236:239], s[60:61]
	s_waitcnt vmcnt(31)
	v_lshlrev_b32_e32 v248, 16, v226
	v_and_b32_e32 v249, 0xffff0000, v226
	v_add_f32_e32 v240, v19, v248
	v_add_f32_e32 v241, v11, v249
	v_lshlrev_b32_e32 v248, 16, v227
	v_and_b32_e32 v249, 0xffff0000, v227
	v_add_f32_e32 v242, v7, v248
	v_add_f32_e32 v243, v3, v249
	s_add_u32 s62, s58, 0x166000
	s_addc_u32 s63, s59, 0
	global_store_dwordx4 v245, v[240:243], s[62:63]
	s_andn2_b64 vcc, exec, s[0:1]
	s_mov_b64 s[0:1], -1
	s_cbranch_vccnz .LBB0_1617
	s_andn2_b64 vcc, exec, s[6:7]
	s_cbranch_vccnz .LBB0_1616
	s_barrier
	s_branch .LBB0_1616
